# full barrier: first arriver of each XCC starts an early L2 write-back
# baseline (speedup 1.0000x reference)
; __device__ __forceinline__ unsigned xb_ld_u(unsigned* p) { return (unsigned)__builtin_amdgcn_readfirstlane((int)__hip_atomic_load(p, RLX_AGENT)); }
; __device__ __forceinline__ unsigned xb_add_u(unsigned* p, unsigned v, int lane) { unsigned r = 0u; if (lane == 0) r = __hip_atomic_fetch_add(p, v, RLX_AGENT); return (unsigned)__builtin_amdgcn_readfirstlane((int)r); }
; #define XB_SPIN_U(cond, bar) do { unsigned _sp = 0; while (cond) { __builtin_amdgcn_s_sleep(1); if (++_sp > XB_SPIN_CAP) { if (lane == 0) atomicAdd(&(bar)[XB_TMO], 1u); break; } } } while (0)
; __device__ __forceinline__ void xcd_barrier(unsigned* bar, volatile __attribute__((address_space(3))) unsigned* st, int wave, int lane) {
;     ...
;         const unsigned old = xb_add_u(&bar[XB_XSUB(x)], 1u, lane), gen = old / nloc;
;         if (old + 1u == (gen + 1u) * nloc) {
;             __builtin_amdgcn_fence(__ATOMIC_RELEASE, "agent");
;             asm volatile("s_waitcnt vmcnt(0)" ::: "memory");
;             const unsigned og = xb_add_u(&bar[XB_TOP], 1u, lane), tg = og / nx;
;             if (og + 1u == (tg + 1u) * nx) (void)xb_add_u(&bar[XB_TOPGEN], 1u, lane);
;             else XB_SPIN_U(xb_ld_u(&bar[XB_TOPGEN]) == tg, bar);
;             __builtin_amdgcn_fence(__ATOMIC_ACQUIRE, "agent");
;             (void)xb_add_u(&bar[XB_XGEN(x)], 1u, lane);
;             asm volatile("s_waitcnt vmcnt(0)" ::: "memory");
;         } else {
;             XB_SPIN_U(xb_ld_u(&bar[XB_XGEN(x)]) == gen, bar);
.LBB0_86:
	s_or_b64 exec, exec, s[6:7]
	v_cvt_f32_u32_e32 v4, v2
	s_waitcnt vmcnt(0) lgkmcnt(0)
	v_readfirstlane_b32 s2, v3
	v_sub_u32_e32 v3, 0, v2
	s_add_i32 s8, s2, 1
	v_rcp_iflag_f32_e32 v4, v4
	s_nop 0
	v_mul_f32_e32 v4, 0x4f7ffffe, v4
	v_cvt_u32_f32_e32 v4, v4
	v_mul_lo_u32 v3, v3, v4
	v_mul_hi_u32 v3, v4, v3
	v_add_u32_e32 v3, v4, v3
	v_mul_hi_u32 v3, s2, v3
	v_mul_lo_u32 v4, v3, v2
	v_sub_u32_e32 v4, s2, v4
	v_add_u32_e32 v5, 1, v3
	v_cmp_ge_u32_e32 vcc, v4, v2
	s_nop 1
	v_cndmask_b32_e32 v3, v3, v5, vcc
	v_sub_u32_e32 v5, v4, v2
	v_cndmask_b32_e32 v4, v4, v5, vcc
	v_add_u32_e32 v5, 1, v3
	v_cmp_ge_u32_e32 vcc, v4, v2
	s_nop 1
	v_cndmask_b32_e32 v3, v3, v5, vcc
	v_mad_u64_u32 v[4:5], s[6:7], v2, v3, v[2:3]
	v_cmp_ne_u32_e32 vcc, s8, v4
	s_and_saveexec_b64 s[6:7], vcc
	s_xor_b64 s[6:7], exec, s[6:7]
	s_cbranch_execz .LBB0_104
	buffer_inv sc1
	v_add_u32_e32 v245, s8, v2
	v_add_u32_e32 v245, -1, v245
	v_cmp_eq_u32_e32 vcc, v245, v4
	s_and_b64 vcc, vcc, exec
	s_cbranch_scc0 .Lnopre_0
	buffer_wbl2 sc1
.Lnopre_0:
	s_add_u32 s14, s1, 0x2400
	s_addc_u32 s15, s0, 0
	s_mov_b32 s2, 0x400001
	s_mov_b64 s[16:17], 0
	s_branch .LBB0_93

; __device__ __forceinline__ unsigned xb_ld_u(unsigned* p) { return (unsigned)__builtin_amdgcn_readfirstlane((int)__hip_atomic_load(p, RLX_AGENT)); }
; __device__ __forceinline__ unsigned xb_add_u(unsigned* p, unsigned v, int lane) { unsigned r = 0u; if (lane == 0) r = __hip_atomic_fetch_add(p, v, RLX_AGENT); return (unsigned)__builtin_amdgcn_readfirstlane((int)r); }
; #define XB_SPIN_U(cond, bar) do { unsigned _sp = 0; while (cond) { __builtin_amdgcn_s_sleep(1); if (++_sp > XB_SPIN_CAP) { if (lane == 0) atomicAdd(&(bar)[XB_TMO], 1u); break; } } } while (0)
; __device__ __forceinline__ void xcd_barrier(unsigned* bar, volatile __attribute__((address_space(3))) unsigned* st, int wave, int lane) {
;     ...
;         const unsigned old = xb_add_u(&bar[XB_XSUB(x)], 1u, lane), gen = old / nloc;
;         if (old + 1u == (gen + 1u) * nloc) {
;             __builtin_amdgcn_fence(__ATOMIC_RELEASE, "agent");
;             asm volatile("s_waitcnt vmcnt(0)" ::: "memory");
;             const unsigned og = xb_add_u(&bar[XB_TOP], 1u, lane), tg = og / nx;
;             if (og + 1u == (tg + 1u) * nx) (void)xb_add_u(&bar[XB_TOPGEN], 1u, lane);
;             else XB_SPIN_U(xb_ld_u(&bar[XB_TOPGEN]) == tg, bar);
;             __builtin_amdgcn_fence(__ATOMIC_ACQUIRE, "agent");
;             (void)xb_add_u(&bar[XB_XGEN(x)], 1u, lane);
;             asm volatile("s_waitcnt vmcnt(0)" ::: "memory");
;         } else {
;             XB_SPIN_U(xb_ld_u(&bar[XB_XGEN(x)]) == gen, bar);
.LBB0_207:
	s_or_b64 exec, exec, s[6:7]
	v_cvt_f32_u32_e32 v4, v2
	s_waitcnt vmcnt(0) lgkmcnt(0)
	v_readfirstlane_b32 s2, v3
	v_sub_u32_e32 v3, 0, v2
	s_add_i32 s8, s2, 1
	v_rcp_iflag_f32_e32 v4, v4
	s_nop 0
	v_mul_f32_e32 v4, 0x4f7ffffe, v4
	v_cvt_u32_f32_e32 v4, v4
	v_mul_lo_u32 v3, v3, v4
	v_mul_hi_u32 v3, v4, v3
	v_add_u32_e32 v3, v4, v3
	v_mul_hi_u32 v3, s2, v3
	v_mul_lo_u32 v4, v3, v2
	v_sub_u32_e32 v4, s2, v4
	v_add_u32_e32 v5, 1, v3
	v_cmp_ge_u32_e32 vcc, v4, v2
	s_nop 1
	v_cndmask_b32_e32 v3, v3, v5, vcc
	v_sub_u32_e32 v5, v4, v2
	v_cndmask_b32_e32 v4, v4, v5, vcc
	v_add_u32_e32 v5, 1, v3
	v_cmp_ge_u32_e32 vcc, v4, v2
	s_nop 1
	v_cndmask_b32_e32 v3, v3, v5, vcc
	v_mad_u64_u32 v[4:5], s[6:7], v2, v3, v[2:3]
	v_cmp_ne_u32_e32 vcc, s8, v4
	s_and_saveexec_b64 s[6:7], vcc
	s_xor_b64 s[6:7], exec, s[6:7]
	s_cbranch_execz .LBB0_225
	buffer_inv sc1
	s_cmp_lg_u32 s100, 0
	s_cbranch_scc1 .Lnopre_1
	v_add_u32_e32 v245, s8, v2
	v_add_u32_e32 v245, -1, v245
	v_cmp_eq_u32_e32 vcc, v245, v4
	s_and_b64 vcc, vcc, exec
	s_cbranch_scc0 .Lnopre_1
	buffer_wbl2 sc1

; __device__ __forceinline__ unsigned xb_ld_u(unsigned* p) { return (unsigned)__builtin_amdgcn_readfirstlane((int)__hip_atomic_load(p, RLX_AGENT)); }
; __device__ __forceinline__ unsigned xb_add_u(unsigned* p, unsigned v, int lane) { unsigned r = 0u; if (lane == 0) r = __hip_atomic_fetch_add(p, v, RLX_AGENT); return (unsigned)__builtin_amdgcn_readfirstlane((int)r); }
; #define XB_SPIN_U(cond, bar) do { unsigned _sp = 0; while (cond) { __builtin_amdgcn_s_sleep(1); if (++_sp > XB_SPIN_CAP) { if (lane == 0) atomicAdd(&(bar)[XB_TMO], 1u); break; } } } while (0)
; __device__ __forceinline__ void xcd_barrier(unsigned* bar, volatile __attribute__((address_space(3))) unsigned* st, int wave, int lane) {
;     ...
;         const unsigned old = xb_add_u(&bar[XB_XSUB(x)], 1u, lane), gen = old / nloc;
;         if (old + 1u == (gen + 1u) * nloc) {
;             __builtin_amdgcn_fence(__ATOMIC_RELEASE, "agent");
;             asm volatile("s_waitcnt vmcnt(0)" ::: "memory");
;             const unsigned og = xb_add_u(&bar[XB_TOP], 1u, lane), tg = og / nx;
;             if (og + 1u == (tg + 1u) * nx) (void)xb_add_u(&bar[XB_TOPGEN], 1u, lane);
;             else XB_SPIN_U(xb_ld_u(&bar[XB_TOPGEN]) == tg, bar);
;             __builtin_amdgcn_fence(__ATOMIC_ACQUIRE, "agent");
;             (void)xb_add_u(&bar[XB_XGEN(x)], 1u, lane);
;             asm volatile("s_waitcnt vmcnt(0)" ::: "memory");
;         } else {
;             XB_SPIN_U(xb_ld_u(&bar[XB_XGEN(x)]) == gen, bar);
.LBB0_321:
	s_or_b64 exec, exec, s[6:7]
	v_cvt_f32_u32_e32 v4, v2
	s_waitcnt vmcnt(0) lgkmcnt(0)
	v_readfirstlane_b32 s2, v3
	v_sub_u32_e32 v3, 0, v2
	s_add_i32 s12, s2, 1
	v_rcp_iflag_f32_e32 v4, v4
	s_nop 0
	v_mul_f32_e32 v4, 0x4f7ffffe, v4
	v_cvt_u32_f32_e32 v4, v4
	v_mul_lo_u32 v3, v3, v4
	v_mul_hi_u32 v3, v4, v3
	v_add_u32_e32 v3, v4, v3
	v_mul_hi_u32 v3, s2, v3
	v_mul_lo_u32 v4, v3, v2
	v_sub_u32_e32 v4, s2, v4
	v_add_u32_e32 v5, 1, v3
	v_cmp_ge_u32_e32 vcc, v4, v2
	s_nop 1
	v_cndmask_b32_e32 v3, v3, v5, vcc
	v_sub_u32_e32 v5, v4, v2
	v_cndmask_b32_e32 v4, v4, v5, vcc
	v_add_u32_e32 v5, 1, v3
	v_cmp_ge_u32_e32 vcc, v4, v2
	s_nop 1
	v_cndmask_b32_e32 v3, v3, v5, vcc
	v_mad_u64_u32 v[4:5], s[6:7], v2, v3, v[2:3]
	v_cmp_ne_u32_e32 vcc, s12, v4
	s_and_saveexec_b64 s[6:7], vcc
	s_xor_b64 s[6:7], exec, s[6:7]
	s_cbranch_execz .LBB0_339
	buffer_inv sc1
	v_add_u32_e32 v245, s12, v2
	v_add_u32_e32 v245, -1, v245
	v_cmp_eq_u32_e32 vcc, v245, v4
	s_and_b64 vcc, vcc, exec
	s_cbranch_scc0 .Lnopre_2
	buffer_wbl2 sc1
.Lnopre_2:
	s_add_u32 s12, s1, 0x2400
	s_addc_u32 s13, s0, 0
	s_mov_b32 s2, 0x400001
	s_mov_b64 s[14:15], 0
	s_branch .LBB0_328

; __device__ __forceinline__ unsigned xb_ld_u(unsigned* p) { return (unsigned)__builtin_amdgcn_readfirstlane((int)__hip_atomic_load(p, RLX_AGENT)); }
; __device__ __forceinline__ unsigned xb_add_u(unsigned* p, unsigned v, int lane) { unsigned r = 0u; if (lane == 0) r = __hip_atomic_fetch_add(p, v, RLX_AGENT); return (unsigned)__builtin_amdgcn_readfirstlane((int)r); }
; #define XB_SPIN_U(cond, bar) do { unsigned _sp = 0; while (cond) { __builtin_amdgcn_s_sleep(1); if (++_sp > XB_SPIN_CAP) { if (lane == 0) atomicAdd(&(bar)[XB_TMO], 1u); break; } } } while (0)
; __device__ __forceinline__ void xcd_barrier(unsigned* bar, volatile __attribute__((address_space(3))) unsigned* st, int wave, int lane) {
;     ...
;         const unsigned old = xb_add_u(&bar[XB_XSUB(x)], 1u, lane), gen = old / nloc;
;         if (old + 1u == (gen + 1u) * nloc) {
;             __builtin_amdgcn_fence(__ATOMIC_RELEASE, "agent");
;             asm volatile("s_waitcnt vmcnt(0)" ::: "memory");
;             const unsigned og = xb_add_u(&bar[XB_TOP], 1u, lane), tg = og / nx;
;             if (og + 1u == (tg + 1u) * nx) (void)xb_add_u(&bar[XB_TOPGEN], 1u, lane);
;             else XB_SPIN_U(xb_ld_u(&bar[XB_TOPGEN]) == tg, bar);
;             __builtin_amdgcn_fence(__ATOMIC_ACQUIRE, "agent");
;             (void)xb_add_u(&bar[XB_XGEN(x)], 1u, lane);
;             asm volatile("s_waitcnt vmcnt(0)" ::: "memory");
;         } else {
;             XB_SPIN_U(xb_ld_u(&bar[XB_XGEN(x)]) == gen, bar);
.LBB0_928:
	s_or_b64 exec, exec, s[6:7]
	v_cvt_f32_u32_e32 v4, v2
	s_waitcnt vmcnt(0) lgkmcnt(0)
	v_readfirstlane_b32 s2, v3
	v_sub_u32_e32 v3, 0, v2
	s_add_i32 s12, s2, 1
	v_rcp_iflag_f32_e32 v4, v4
	s_nop 0
	v_mul_f32_e32 v4, 0x4f7ffffe, v4
	v_cvt_u32_f32_e32 v4, v4
	v_mul_lo_u32 v3, v3, v4
	v_mul_hi_u32 v3, v4, v3
	v_add_u32_e32 v3, v4, v3
	v_mul_hi_u32 v3, s2, v3
	v_mul_lo_u32 v4, v3, v2
	v_sub_u32_e32 v4, s2, v4
	v_add_u32_e32 v5, 1, v3
	v_cmp_ge_u32_e32 vcc, v4, v2
	s_nop 1
	v_cndmask_b32_e32 v3, v3, v5, vcc
	v_sub_u32_e32 v5, v4, v2
	v_cndmask_b32_e32 v4, v4, v5, vcc
	v_add_u32_e32 v5, 1, v3
	v_cmp_ge_u32_e32 vcc, v4, v2
	s_nop 1
	v_cndmask_b32_e32 v3, v3, v5, vcc
	v_mad_u64_u32 v[4:5], s[6:7], v2, v3, v[2:3]
	v_cmp_ne_u32_e32 vcc, s12, v4
	s_and_saveexec_b64 s[6:7], vcc
	s_xor_b64 s[6:7], exec, s[6:7]
	s_cbranch_execz .LBB0_946
	buffer_inv sc1
	s_cmp_lg_u32 s100, 0
	s_cbranch_scc1 .Lnopre_7
	v_add_u32_e32 v245, s12, v2
	v_add_u32_e32 v245, -1, v245
	v_cmp_eq_u32_e32 vcc, v245, v4
	s_and_b64 vcc, vcc, exec
	s_cbranch_scc0 .Lnopre_7
	buffer_wbl2 sc1
